# S21 with the eight packed-f32 FMAs of the second half-step replaced by sixteen scalar v_fmamk (same arithmetic)
# baseline (speedup 1.0000x reference)
; #define SBAR() __builtin_amdgcn_sched_barrier(0)
; __device__ __forceinline__ void partialSM(f32x16& p0, f32x16& p1, float& m_reg, float& mn, float& alpha) {
;   constexpr float C = SCALE * 1.4426950408889634f;
;   float pmax = p0[0]; for (int r = 1; r < 16; ++r) pmax = fmaxf(pmax, p0[r]); for (int r = 0; r < 16; ++r) pmax = fmaxf(pmax, p1[r]);
;   { auto rr = __builtin_amdgcn_permlane32_swap(__float_as_uint(pmax), __float_as_uint(pmax), false, false);
;     pmax = fmaxf(__uint_as_float(rr[0]), __uint_as_float(rr[1])); }
;   if (__builtin_expect(__all(pmax - m_reg <= THR / SCALE), 1)) { mn = m_reg; alpha = 1.f; }
;   else { mn = fmaxf(m_reg, pmax); alpha = __builtin_amdgcn_exp2f((m_reg - mn) * C); m_reg = mn; }
;   float mnC = -mn * C;
;   for (int r = 0; r < 16; ++r) p0[r] = fmaf(p0[r], C, mnC); for (int r = 0; r < 16; ++r) p1[r] = fmaf(p1[r], C, mnC);
;   for (int r = 0; r < 16; ++r) p0[r] = __builtin_amdgcn_exp2f(p0[r]);
; }
; __device__ __forceinline__ void pv_mma(f32x16& od, const VFrag& f, bf16x8 pa0, bf16x8 pa1, bf16x8 pa2, bf16x8 pa3) {
;     ...
;   od = __builtin_amdgcn_mfma_f32_32x32x16_bf16(pa0, PK(f.l0, f.h0), od, 0, 0, 0);
;   od = __builtin_amdgcn_mfma_f32_32x32x16_bf16(pa1, PK(f.l1, f.h1), od, 0, 0, 0);
;   od = __builtin_amdgcn_mfma_f32_32x32x16_bf16(pa2, PK(f.l2, f.h2), od, 0, 0, 0);
;   od = __builtin_amdgcn_mfma_f32_32x32x16_bf16(pa3, PK(f.l3, f.h3), od, 0, 0, 0);
;     ...
; }
; __device__ __forceinline__ void pv_d0(f32x16* o, int vb, bf16x8 pa0, bf16x8 pa1, bf16x8 pa2, bf16x8 pa3) {
;   VFrag fa, fb;
;   v_frag_read<0>(fa, vb);
;   asm volatile("s_waitcnt lgkmcnt(0)" ::: "memory"); SBAR();
;   v_frag_read<1>(fb, vb); SBAR();
;   pv_mma(o[0], fa, pa0, pa1, pa2, pa3); SBAR();
;   asm volatile("s_waitcnt lgkmcnt(0)" ::: "memory"); SBAR();
;   v_frag_read<2>(fa, vb); SBAR();
;   pv_mma(o[1], fb, pa0, pa1, pa2, pa3); SBAR();
;   asm volatile("s_waitcnt lgkmcnt(0)" ::: "memory"); SBAR();
;   v_frag_read<3>(fb, vb); SBAR();
;   pv_mma(o[2], fa, pa0, pa1, pa2, pa3); SBAR();
;   asm volatile("s_waitcnt lgkmcnt(0)" ::: "memory"); SBAR();
;   pv_mma(o[3], fb, pa0, pa1, pa2, pa3);
; }
.LBB0_776:
	v_mov_b32_e32 v100, v99
	s_nop 1
	v_permlane32_swap_b32_e32 v99, v100
	v_cvt_pk_bf16_f32 v102, v192, v193
	v_cvt_pk_bf16_f32 v103, v194, v195
	v_cvt_pk_bf16_f32 v104, v196, v197
	v_cvt_pk_bf16_f32 v105, v198, v199
	s_waitcnt lgkmcnt(8)
	v_mfma_f32_32x32x16_bf16 v[66:81], v[174:177], v[114:117], v[66:81]
	v_cvt_pk_bf16_f32 v106, v200, v201
	v_cvt_pk_bf16_f32 v107, v202, v203
	v_cvt_pk_bf16_f32 v108, v204, v205
	v_cvt_pk_bf16_f32 v109, v206, v207
	v_cvt_pk_bf16_f32 v110, v210, v211
	v_cvt_pk_bf16_f32 v111, v212, v213
	v_cvt_pk_bf16_f32 v112, v214, v215
	v_cvt_pk_bf16_f32 v113, v149, v150
	v_cvt_pk_bf16_f32 v134, v151, v186
	v_cvt_pk_bf16_f32 v135, v187, v188
	v_cvt_pk_bf16_f32 v136, v189, v208
	v_cvt_pk_bf16_f32 v137, v209, v148
	v_permlane32_swap_b32_e32 v102, v104
	v_permlane32_swap_b32_e32 v103, v105
	v_permlane32_swap_b32_e32 v106, v108
	v_permlane32_swap_b32_e32 v107, v109
	v_permlane32_swap_b32_e32 v110, v112
	v_permlane32_swap_b32_e32 v111, v113
	v_permlane32_swap_b32_e32 v134, v136
	v_permlane32_swap_b32_e32 v135, v137
	ds_read_b64_tr_b16 v[204:205], v244 offset:0x200
	ds_read_b64_tr_b16 v[206:207], v244 offset:0xa00
	ds_read_b64_tr_b16 v[208:209], v244 offset:0x1200
	ds_read_b64_tr_b16 v[210:211], v244 offset:0x1a00
	ds_read_b64_tr_b16 v[212:213], v244 offset:0x2200
	ds_read_b64_tr_b16 v[214:215], v244 offset:0x2a00
	ds_read_b64_tr_b16 v[216:217], v244 offset:0x3200
	ds_read_b64_tr_b16 v[218:219], v244 offset:0x3a00
	s_waitcnt lgkmcnt(14)
	v_mfma_f32_32x32x16_bf16 v[18:33], v[102:105], v[228:231], v[18:33]
	v_max_f32_e32 v245, v83, v83
	v_max_f32_e32 v246, v82, v82
	v_max_f32_e32 v245, v246, v245
	v_max3_f32 v245, v245, v84, v85
	v_max3_f32 v245, v245, v86, v87
	v_max3_f32 v245, v245, v88, v89
	v_max3_f32 v245, v245, v90, v91
	v_max3_f32 v245, v245, v92, v93
	s_waitcnt lgkmcnt(12)
	v_mfma_f32_32x32x16_bf16 v[18:33], v[106:109], v[232:235], v[18:33]
	v_max3_f32 v245, v245, v94, v95
	v_max3_f32 v245, v245, v96, v97
	v_max3_f32 v245, v245, v66, v67
	v_max3_f32 v245, v245, v68, v69
	v_max3_f32 v245, v245, v70, v71
	v_max3_f32 v245, v245, v72, v73
	v_max3_f32 v245, v245, v74, v75
	v_max3_f32 v245, v245, v76, v77
	s_waitcnt lgkmcnt(10)
	v_mfma_f32_32x32x16_bf16 v[18:33], v[110:113], v[236:239], v[18:33]
	v_max3_f32 v245, v245, v78, v79
	v_max3_f32 v245, v245, v80, v81
	v_mov_b32_e32 v246, v245
	s_nop 1
	v_permlane32_swap_b32_e32 v245, v246
	v_max_f32_e32 v246, v246, v246
	v_max_f32_e32 v245, v245, v245
	v_max_f32_e32 v245, v245, v246
	v_sub_f32_e32 v246, v245, v133
	s_waitcnt lgkmcnt(8)
	v_mfma_f32_32x32x16_bf16 v[18:33], v[134:137], v[240:243], v[18:33]
	v_cmp_ge_f32_e32 vcc, s63, v246
	v_max_f32_e32 v246, v133, v133
	v_max_f32_e32 v245, v246, v245
	v_sub_f32_e32 v246, v133, v245
	v_mul_f32_e32 v246, 0x3e38aa3b, v246
	v_exp_f32_e32 v246, v246
	s_cmp_eq_u64 vcc, exec
	s_cselect_b64 s[0:1], -1, 0
	v_cndmask_b32_e64 v247, v246, 1.0, s[0:1]
	ds_read_b64_tr_b16 v[228:229], v244 offset:0x400
	ds_read_b64_tr_b16 v[230:231], v244 offset:0xc00
	ds_read_b64_tr_b16 v[232:233], v244 offset:0x1400
	ds_read_b64_tr_b16 v[234:235], v244 offset:0x1c00
	ds_read_b64_tr_b16 v[236:237], v244 offset:0x2400
	ds_read_b64_tr_b16 v[238:239], v244 offset:0x2c00
	ds_read_b64_tr_b16 v[240:241], v244 offset:0x3400
	ds_read_b64_tr_b16 v[242:243], v244 offset:0x3c00
	v_cndmask_b32_e64 v174, v245, v133, s[0:1]
	v_mul_f32_e32 v98, 0xbe38aa3b, v174
	s_waitcnt lgkmcnt(14)
	v_mfma_f32_32x32x16_bf16 v[50:65], v[102:105], v[204:207], v[50:65]
	v_fmamk_f32 v82, v82, 0x3e38aa3b, v98
	v_fmamk_f32 v83, v83, 0x3e38aa3b, v98
	v_fmamk_f32 v84, v84, 0x3e38aa3b, v98
	v_fmamk_f32 v85, v85, 0x3e38aa3b, v98
	s_waitcnt lgkmcnt(12)
	v_mfma_f32_32x32x16_bf16 v[50:65], v[106:109], v[208:211], v[50:65]
	v_fmamk_f32 v86, v86, 0x3e38aa3b, v98
	v_fmamk_f32 v87, v87, 0x3e38aa3b, v98
	v_fmamk_f32 v88, v88, 0x3e38aa3b, v98
	v_fmamk_f32 v89, v89, 0x3e38aa3b, v98
	s_waitcnt lgkmcnt(10)
	v_mfma_f32_32x32x16_bf16 v[50:65], v[110:113], v[212:215], v[50:65]
	v_fmamk_f32 v90, v90, 0x3e38aa3b, v98
	v_fmamk_f32 v91, v91, 0x3e38aa3b, v98
	v_fmamk_f32 v92, v92, 0x3e38aa3b, v98
	v_fmamk_f32 v93, v93, 0x3e38aa3b, v98
	s_waitcnt lgkmcnt(8)
	v_mfma_f32_32x32x16_bf16 v[50:65], v[134:137], v[216:219], v[50:65]
	v_fmamk_f32 v94, v94, 0x3e38aa3b, v98
	v_fmamk_f32 v95, v95, 0x3e38aa3b, v98
	v_fmamk_f32 v96, v96, 0x3e38aa3b, v98
	v_fmamk_f32 v97, v97, 0x3e38aa3b, v98
	ds_read_b64_tr_b16 v[204:205], v244 offset:0x600
	ds_read_b64_tr_b16 v[206:207], v244 offset:0xe00
	ds_read_b64_tr_b16 v[208:209], v244 offset:0x1600
	ds_read_b64_tr_b16 v[210:211], v244 offset:0x1e00
	ds_read_b64_tr_b16 v[212:213], v244 offset:0x2600
	ds_read_b64_tr_b16 v[214:215], v244 offset:0x2e00
	ds_read_b64_tr_b16 v[216:217], v244 offset:0x3600
	ds_read_b64_tr_b16 v[218:219], v244 offset:0x3e00
	s_waitcnt lgkmcnt(14)
	v_mfma_f32_32x32x16_bf16 v[34:49], v[102:105], v[228:231], v[34:49]
	v_fmamk_f32 v80, v80, 0x3e38aa3b, v98
	v_fmamk_f32 v81, v81, 0x3e38aa3b, v98
	v_fmamk_f32 v78, v78, 0x3e38aa3b, v98
	v_fmamk_f32 v79, v79, 0x3e38aa3b, v98
	s_waitcnt lgkmcnt(12)
	v_mfma_f32_32x32x16_bf16 v[34:49], v[106:109], v[232:235], v[34:49]
	v_fmamk_f32 v76, v76, 0x3e38aa3b, v98
	v_fmamk_f32 v77, v77, 0x3e38aa3b, v98
	v_fmamk_f32 v74, v74, 0x3e38aa3b, v98
	v_fmamk_f32 v75, v75, 0x3e38aa3b, v98
	v_fmamk_f32 v72, v72, 0x3e38aa3b, v98
	v_fmamk_f32 v73, v73, 0x3e38aa3b, v98
	s_waitcnt lgkmcnt(10)
	v_mfma_f32_32x32x16_bf16 v[34:49], v[110:113], v[236:239], v[34:49]
	v_fmamk_f32 v70, v70, 0x3e38aa3b, v98
	v_fmamk_f32 v71, v71, 0x3e38aa3b, v98
	v_fmamk_f32 v68, v68, 0x3e38aa3b, v98
	v_fmamk_f32 v69, v69, 0x3e38aa3b, v98
	v_fmamk_f32 v66, v66, 0x3e38aa3b, v98
	v_fmamk_f32 v67, v67, 0x3e38aa3b, v98
	s_waitcnt lgkmcnt(8)
	v_mfma_f32_32x32x16_bf16 v[34:49], v[134:137], v[240:243], v[34:49]
	v_exp_f32_e32 v175, v82
	v_exp_f32_e32 v177, v83
	v_exp_f32_e32 v192, v84
	s_waitcnt lgkmcnt(6)
	v_mfma_f32_32x32x16_bf16 v[2:17], v[102:105], v[204:207], v[2:17]
	v_mov_b32_e32 v205, v247
	v_exp_f32_e32 v204, v97
	v_exp_f32_e32 v195, v85
	v_exp_f32_e32 v196, v86
	v_exp_f32_e32 v199, v87
	v_exp_f32_e32 v200, v88
	s_waitcnt lgkmcnt(4)
	v_mfma_f32_32x32x16_bf16 v[2:17], v[106:109], v[208:211], v[2:17]
	v_exp_f32_e32 v203, v89
	v_exp_f32_e32 v176, v90
	v_exp_f32_e32 v193, v91
	v_exp_f32_e32 v194, v92
	s_waitcnt lgkmcnt(2)
	v_mfma_f32_32x32x16_bf16 v[2:17], v[110:113], v[212:215], v[2:17]
	v_exp_f32_e32 v197, v93
	v_exp_f32_e32 v198, v94
	v_exp_f32_e32 v201, v95
	v_exp_f32_e32 v202, v96
	s_waitcnt lgkmcnt(0)
	v_mfma_f32_32x32x16_bf16 v[2:17], v[134:137], v[216:219], v[2:17]
	v_add_u32_e32 v245, s100, v169
	v_add_u32_e32 v246, s100, v170
	v_add_u32_e32 v247, s100, v171
	v_add_u32_e32 v255, s100, v172
	v_cmp_gt_f32_e32 vcc, 1.0, v205
	s_cbranch_vccz .LBB0_780
	s_and_saveexec_b64 s[12:13], s[40:41]
	ds_write_b32 v162, v205 offset:128
	s_or_b64 exec, exec, s[12:13]
	s_waitcnt lgkmcnt(0)
	v_add_u32_e32 v101, s18, v140
	ds_read_b128 v[102:105], v101 offset:224
	ds_read_b128 v[106:109], v101 offset:192
	ds_read_b128 v[110:113], v101 offset:160
	ds_read_b128 v[134:137], v101 offset:128
	s_waitcnt lgkmcnt(0)
	v_pk_mul_f32 v[30:31], v[30:31], v[102:103]
	v_pk_mul_f32 v[26:27], v[26:27], v[106:107]
	v_pk_mul_f32 v[22:23], v[22:23], v[110:111]
	v_pk_mul_f32 v[32:33], v[32:33], v[104:105]
	v_pk_mul_f32 v[28:29], v[28:29], v[108:109]
	v_pk_mul_f32 v[24:25], v[24:25], v[112:113]
	v_pk_mul_f32 v[20:21], v[20:21], v[136:137]
	v_pk_mul_f32 v[18:19], v[18:19], v[134:135]
	v_pk_mul_f32 v[62:63], v[62:63], v[102:103]
	v_pk_mul_f32 v[58:59], v[58:59], v[106:107]
	v_pk_mul_f32 v[54:55], v[54:55], v[110:111]
	v_pk_mul_f32 v[64:65], v[64:65], v[104:105]
	v_pk_mul_f32 v[60:61], v[60:61], v[108:109]
	v_pk_mul_f32 v[56:57], v[56:57], v[112:113]
	v_pk_mul_f32 v[52:53], v[52:53], v[136:137]
	v_pk_mul_f32 v[50:51], v[50:51], v[134:135]
	v_pk_mul_f32 v[46:47], v[46:47], v[102:103]
	v_pk_mul_f32 v[42:43], v[42:43], v[106:107]
	v_pk_mul_f32 v[38:39], v[38:39], v[110:111]
	v_pk_mul_f32 v[48:49], v[48:49], v[104:105]
	v_pk_mul_f32 v[44:45], v[44:45], v[108:109]
	v_pk_mul_f32 v[40:41], v[40:41], v[112:113]
	v_pk_mul_f32 v[36:37], v[36:37], v[136:137]
	v_pk_mul_f32 v[34:35], v[34:35], v[134:135]
	v_pk_mul_f32 v[14:15], v[14:15], v[102:103]
	v_pk_mul_f32 v[10:11], v[10:11], v[106:107]
	v_pk_mul_f32 v[6:7], v[6:7], v[110:111]
	v_pk_mul_f32 v[16:17], v[16:17], v[104:105]
	v_pk_mul_f32 v[12:13], v[12:13], v[108:109]
	v_pk_mul_f32 v[8:9], v[8:9], v[112:113]
	v_pk_mul_f32 v[4:5], v[4:5], v[136:137]
	v_pk_mul_f32 v[2:3], v[2:3], v[134:135]
